# wo-projection residual epilogue: the 10 later gnext/scale/shift loads batched behind the first two, counted waits keep the original guarantees
# baseline (speedup 1.0000x reference)
.LBB0_447:
	s_or_b64 exec, exec, s[8:9]
	s_lshl_b32 s0, s61, 10
	s_ashr_i32 s1, s0, 31
	v_readlane_b32 s12, v253, 40
	s_lshl_b64 s[0:1], s[0:1], 2
	v_readlane_b32 s20, v253, 48
	v_readlane_b32 s21, v253, 49
	s_add_u32 s0, s20, s0
	s_addc_u32 s1, s21, s1
	s_add_u32 s8, s6, 0x4000
	s_addc_u32 s9, s7, 0
	v_lshlrev_b64 v[8:9], 2, v[148:149]
	v_lshl_add_u64 v[4:5], s[8:9], 0, v[8:9]
	s_waitcnt lgkmcnt(0)
	s_barrier
	v_lshl_add_u64 v[142:143], s[0:1], 0, v[8:9]
	global_load_dwordx4 v[4:7], v[4:5], off
	s_add_u32 s6, s6, 0x3000
	global_load_dwordx4 v[0:3], v[142:143], off
	s_addc_u32 s7, s7, 0
	v_lshl_add_u64 v[250:251], s[8:9], 0, v[8:9]
	v_lshl_add_u64 v[180:181], s[6:7], 0, v[8:9]
	global_load_dwordx4 v[214:217], v[250:251], off offset:64
	global_load_dwordx4 v[218:221], v[142:143], off offset:64
	global_load_dwordx4 v[222:225], v[250:251], off offset:512
	global_load_dwordx4 v[226:229], v[142:143], off offset:512
	global_load_dwordx4 v[230:233], v[142:143], off offset:576
	global_load_dwordx4 v[234:237], v[250:251], off offset:576
	global_load_dwordx4 v[238:241], v[180:181], off offset:512
	global_load_dwordx4 v[242:245], v[180:181], off offset:576
	global_load_dwordx4 v[246:249], v[180:181], off
	global_load_dwordx4 v[176:179], v[180:181], off offset:64
	v_readlane_b32 s0, v254, 41
	v_readlane_b32 s1, v254, 42
	v_readlane_b32 s13, v253, 41
	v_readlane_b32 s14, v253, 42
	v_readlane_b32 s15, v253, 43
	v_readlane_b32 s16, v253, 44
	v_readlane_b32 s17, v253, 45
	v_readlane_b32 s18, v253, 46
	v_readlane_b32 s19, v253, 47
	v_readlane_b32 s22, v253, 50
	v_readlane_b32 s23, v253, 51
	v_readlane_b32 s24, v253, 52
	v_readlane_b32 s25, v253, 53
	v_readlane_b32 s26, v253, 54
	v_readlane_b32 s27, v253, 55
	s_waitcnt vmcnt(11)
	v_pk_add_f32 v[4:5], v[4:5], 1.0 op_sel_hi:[1,0]
	v_pk_add_f32 v[6:7], v[6:7], 1.0 op_sel_hi:[1,0]
	s_waitcnt vmcnt(10)
	v_pk_mul_f32 v[132:133], v[0:1], v[4:5]
	v_lshl_add_u64 v[0:1], s[6:7], 0, v[8:9]
	v_or_b32_e32 v8, 16, v148
	v_ashrrev_i32_e32 v9, 31, v8
	v_lshlrev_b64 v[12:13], 2, v[8:9]
	v_lshl_add_u64 v[8:9], s[8:9], 0, v[12:13]
	v_pk_mul_f32 v[130:131], v[2:3], v[6:7]
	s_waitcnt vmcnt(9)
	v_pk_add_f32 v[8:9], v[214:215], 1.0 op_sel_hi:[1,0]
	v_pk_add_f32 v[10:11], v[216:217], 1.0 op_sel_hi:[1,0]
	s_waitcnt vmcnt(8)
	v_pk_mul_f32 v[136:137], v[218:219], v[8:9]
	v_lshl_add_u64 v[4:5], s[6:7], 0, v[12:13]
	v_or_b32_e32 v12, 0x80, v148
	v_ashrrev_i32_e32 v13, 31, v12
	v_lshlrev_b64 v[144:145], 2, v[12:13]
	v_lshl_add_u64 v[12:13], s[8:9], 0, v[144:145]
	v_pk_mul_f32 v[134:135], v[220:221], v[10:11]
	s_waitcnt vmcnt(7)
	v_pk_add_f32 v[12:13], v[222:223], 1.0 op_sel_hi:[1,0]
	v_pk_add_f32 v[14:15], v[224:225], 1.0 op_sel_hi:[1,0]
	s_waitcnt vmcnt(6)
	v_pk_mul_f32 v[140:141], v[226:227], v[12:13]
	v_lshl_add_u64 v[8:9], s[6:7], 0, v[144:145]
	v_or_b32_e32 v144, 0x90, v148
	v_ashrrev_i32_e32 v145, 31, v144
	v_lshlrev_b64 v[148:149], 2, v[144:145]
	v_pk_mul_f32 v[138:139], v[228:229], v[14:15]
	v_lshl_add_u64 v[142:143], s[8:9], 0, v[148:149]
	s_waitcnt vmcnt(4)
	v_pk_add_f32 v[144:145], v[236:237], 1.0 op_sel_hi:[1,0]
	v_pk_add_f32 v[164:165], v[234:235], 1.0 op_sel_hi:[1,0]
	v_pk_mul_f32 v[142:143], v[232:233], v[144:145]
	v_pk_mul_f32 v[144:145], v[230:231], v[164:165]
	v_lshl_add_u64 v[12:13], s[6:7], 0, v[148:149]
	v_add_u32_e32 v148, s28, v113
	v_lshl_add_u32 v113, v113, 2, 0
	v_add_u32_e32 v113, 0x1000, v113
	ds_read2_b32 v[174:175], v113 offset1:16
	v_ashrrev_i32_e32 v149, 31, v148
	v_lshlrev_b64 v[164:165], 11, v[148:149]
	v_lshl_add_u64 v[164:165], s[0:1], 0, v[164:165]
	v_lshl_add_u64 v[164:165], v[164:165], 0, v[146:147]
	s_waitcnt lgkmcnt(0)
	v_pk_mul_f32 v[114:115], v[114:115], v[174:175] op_sel_hi:[1,0]
	v_pk_mul_f32 v[116:117], v[116:117], v[174:175] op_sel_hi:[1,0]
	v_pk_mul_f32 v[126:127], v[126:127], v[174:175] op_sel_hi:[1,0]
	v_pk_mul_f32 v[128:129], v[128:129], v[174:175] op_sel_hi:[1,0]
	v_pk_mul_f32 v[122:123], v[122:123], v[174:175] op_sel_hi:[1,0]
	v_pk_mul_f32 v[124:125], v[124:125], v[174:175] op_sel_hi:[1,0]
	v_pk_mul_f32 v[118:119], v[118:119], v[174:175] op_sel_hi:[1,0]
	v_pk_mul_f32 v[120:121], v[120:121], v[174:175] op_sel_hi:[1,0]
	s_waitcnt vmcnt(3)
	v_pk_fma_f32 v[118:119], v[140:141], v[118:119], v[238:239]
	v_pk_fma_f32 v[120:121], v[138:139], v[120:121], v[240:241]
	s_waitcnt vmcnt(2)
	v_pk_fma_f32 v[116:117], v[142:143], v[116:117], v[244:245]
	v_pk_fma_f32 v[114:115], v[144:145], v[114:115], v[242:243]
	s_waitcnt vmcnt(1)
	v_pk_fma_f32 v[128:129], v[130:131], v[128:129], v[248:249]
	v_cvt_pk_bf16_f32 v114, v114, v115
	v_cvt_pk_bf16_f32 v115, v116, v117
	v_mov_b32_e32 v116, v175
	global_store_dwordx2 v[164:165], v[114:115], off offset:288
	v_add_u32_e32 v114, 16, v148
	v_pk_mul_f32 v[92:93], v[92:93], v[116:117] op_sel_hi:[1,0]
	v_pk_mul_f32 v[94:95], v[94:95], v[116:117] op_sel_hi:[1,0]
	v_ashrrev_i32_e32 v115, 31, v114
	v_pk_fma_f32 v[94:95], v[142:143], v[94:95], v[244:245]
	v_pk_fma_f32 v[92:93], v[144:145], v[92:93], v[242:243]
	v_lshlrev_b64 v[114:115], 11, v[114:115]
	v_cvt_pk_bf16_f32 v92, v92, v93
	v_cvt_pk_bf16_f32 v93, v94, v95
	ds_read2_b32 v[94:95], v113 offset0:32 offset1:48
	v_lshl_add_u64 v[114:115], s[0:1], 0, v[114:115]
	v_lshl_add_u64 v[114:115], v[114:115], 0, v[146:147]
	global_store_dwordx2 v[114:115], v[92:93], off offset:288
	v_add_u32_e32 v92, 32, v148
	v_ashrrev_i32_e32 v93, 31, v92
	v_lshlrev_b64 v[92:93], 11, v[92:93]
	s_waitcnt lgkmcnt(0)
	v_pk_mul_f32 v[76:77], v[76:77], v[94:95] op_sel_hi:[1,0]
	v_pk_mul_f32 v[78:79], v[78:79], v[94:95] op_sel_hi:[1,0]
	v_lshl_add_u64 v[92:93], s[0:1], 0, v[92:93]
	v_pk_fma_f32 v[78:79], v[142:143], v[78:79], v[244:245]
	v_pk_fma_f32 v[76:77], v[144:145], v[76:77], v[242:243]
	v_lshl_add_u64 v[92:93], v[92:93], 0, v[146:147]
	v_cvt_pk_bf16_f32 v76, v76, v77
	v_cvt_pk_bf16_f32 v77, v78, v79
	v_mov_b32_e32 v78, v95
	global_store_dwordx2 v[92:93], v[76:77], off offset:288
	v_add_u32_e32 v76, 48, v148
	v_pk_mul_f32 v[64:65], v[64:65], v[78:79] op_sel_hi:[1,0]
	v_pk_mul_f32 v[66:67], v[66:67], v[78:79] op_sel_hi:[1,0]
	v_ashrrev_i32_e32 v77, 31, v76
	v_pk_fma_f32 v[66:67], v[142:143], v[66:67], v[244:245]
	v_pk_fma_f32 v[64:65], v[144:145], v[64:65], v[242:243]
	v_lshlrev_b64 v[76:77], 11, v[76:77]
	v_cvt_pk_bf16_f32 v64, v64, v65
	v_cvt_pk_bf16_f32 v65, v66, v67
	ds_read2_b32 v[66:67], v113 offset0:128 offset1:144
	v_lshl_add_u64 v[76:77], s[0:1], 0, v[76:77]
	v_lshl_add_u64 v[76:77], v[76:77], 0, v[146:147]
	global_store_dwordx2 v[76:77], v[64:65], off offset:288
	v_add_u32_e32 v64, 0x80, v148
	v_ashrrev_i32_e32 v65, 31, v64
	v_lshlrev_b64 v[64:65], 11, v[64:65]
	s_waitcnt lgkmcnt(0)
	v_pk_mul_f32 v[44:45], v[44:45], v[66:67] op_sel_hi:[1,0]
	v_pk_mul_f32 v[46:47], v[46:47], v[66:67] op_sel_hi:[1,0]
	v_lshl_add_u64 v[64:65], s[0:1], 0, v[64:65]
	v_pk_fma_f32 v[46:47], v[142:143], v[46:47], v[244:245]
	v_pk_fma_f32 v[44:45], v[144:145], v[44:45], v[242:243]
	v_lshl_add_u64 v[64:65], v[64:65], 0, v[146:147]
	v_cvt_pk_bf16_f32 v44, v44, v45
	v_cvt_pk_bf16_f32 v45, v46, v47
	global_store_dwordx2 v[64:65], v[44:45], off offset:288
	v_add_u32_e32 v44, 0x90, v148
	v_ashrrev_i32_e32 v45, 31, v44
	v_mov_b32_e32 v46, v67
	v_pk_mul_f32 v[108:109], v[108:109], v[116:117] op_sel_hi:[1,0]
	v_pk_mul_f32 v[110:111], v[110:111], v[116:117] op_sel_hi:[1,0]
	v_lshlrev_b64 v[44:45], 11, v[44:45]
	v_pk_mul_f32 v[48:49], v[48:49], v[46:47] op_sel_hi:[1,0]
	v_pk_mul_f32 v[50:51], v[50:51], v[46:47] op_sel_hi:[1,0]
	v_pk_fma_f32 v[110:111], v[130:131], v[110:111], v[248:249]
	v_pk_fma_f32 v[108:109], v[132:133], v[108:109], v[246:247]
	v_lshl_add_u64 v[44:45], s[0:1], 0, v[44:45]
	v_pk_fma_f32 v[50:51], v[130:131], v[50:51], v[248:249]
	v_pk_fma_f32 v[48:49], v[132:133], v[48:49], v[246:247]
	v_cvt_pk_bf16_f32 v108, v108, v109
	v_cvt_pk_bf16_f32 v109, v110, v111
	v_lshl_add_u64 v[44:45], v[44:45], 0, v[146:147]
	v_cvt_pk_bf16_f32 v48, v48, v49
	v_cvt_pk_bf16_f32 v49, v50, v51
	global_store_dwordx2 v[114:115], v[108:109], off
	v_pk_mul_f32 v[104:105], v[104:105], v[116:117] op_sel_hi:[1,0]
	v_pk_mul_f32 v[106:107], v[106:107], v[116:117] op_sel_hi:[1,0]
	global_store_dwordx2 v[44:45], v[48:49], off
	v_pk_mul_f32 v[48:49], v[152:153], v[46:47] op_sel_hi:[1,0]
	v_pk_mul_f32 v[42:43], v[42:43], v[46:47] op_sel_hi:[1,0]
	s_waitcnt vmcnt(7)
	v_pk_fma_f32 v[106:107], v[134:135], v[106:107], v[178:179]
	v_pk_fma_f32 v[104:105], v[136:137], v[104:105], v[176:177]
	v_pk_fma_f32 v[42:43], v[134:135], v[42:43], v[178:179]
	v_pk_fma_f32 v[48:49], v[136:137], v[48:49], v[176:177]
	v_cvt_pk_bf16_f32 v104, v104, v105
	v_cvt_pk_bf16_f32 v105, v106, v107
	v_cvt_pk_bf16_f32 v48, v48, v49
	v_cvt_pk_bf16_f32 v49, v42, v43
	global_store_dwordx2 v[114:115], v[104:105], off offset:32
	v_pk_mul_f32 v[100:101], v[100:101], v[116:117] op_sel_hi:[1,0]
	v_pk_mul_f32 v[102:103], v[102:103], v[116:117] op_sel_hi:[1,0]
	global_store_dwordx2 v[44:45], v[48:49], off offset:32
	v_pk_mul_f32 v[42:43], v[172:173], v[46:47] op_sel_hi:[1,0]
	v_pk_mul_f32 v[48:49], v[160:161], v[46:47] op_sel_hi:[1,0]
	v_pk_fma_f32 v[102:103], v[138:139], v[102:103], v[240:241]
	v_pk_fma_f32 v[100:101], v[140:141], v[100:101], v[238:239]
	v_pk_fma_f32 v[48:49], v[138:139], v[48:49], v[240:241]
	v_pk_fma_f32 v[42:43], v[140:141], v[42:43], v[238:239]
	v_cvt_pk_bf16_f32 v100, v100, v101
	v_cvt_pk_bf16_f32 v101, v102, v103
	v_cvt_pk_bf16_f32 v42, v42, v43
	v_cvt_pk_bf16_f32 v43, v48, v49
	global_store_dwordx2 v[114:115], v[100:101], off offset:256
	global_store_dwordx2 v[44:45], v[42:43], off offset:256
	v_pk_mul_f32 v[42:43], v[170:171], v[46:47] op_sel_hi:[1,0]
	v_pk_mul_f32 v[46:47], v[158:159], v[46:47] op_sel_hi:[1,0]
	v_pk_fma_f32 v[42:43], v[144:145], v[42:43], v[242:243]
	v_pk_fma_f32 v[46:47], v[142:143], v[46:47], v[244:245]
	v_cvt_pk_bf16_f32 v42, v42, v43
	v_cvt_pk_bf16_f32 v43, v46, v47
	global_store_dwordx2 v[44:45], v[42:43], off offset:288
	ds_read2_b32 v[44:45], v113 offset0:160 offset1:176
	v_add_u32_e32 v42, 0xa0, v148
	v_ashrrev_i32_e32 v43, 31, v42
	v_lshlrev_b64 v[42:43], 11, v[42:43]
	v_lshl_add_u64 v[42:43], s[0:1], 0, v[42:43]
	s_waitcnt lgkmcnt(0)
	v_pk_mul_f32 v[46:47], v[156:157], v[44:45] op_sel_hi:[1,0]
	v_pk_mul_f32 v[40:41], v[40:41], v[44:45] op_sel_hi:[1,0]
	v_pk_fma_f32 v[46:47], v[132:133], v[46:47], v[246:247]
	v_pk_fma_f32 v[40:41], v[130:131], v[40:41], v[248:249]
	v_cvt_pk_bf16_f32 v46, v46, v47
	v_cvt_pk_bf16_f32 v47, v40, v41
	v_pk_mul_f32 v[40:41], v[154:155], v[44:45] op_sel_hi:[1,0]
	v_pk_mul_f32 v[36:37], v[36:37], v[44:45] op_sel_hi:[1,0]
	v_pk_fma_f32 v[40:41], v[136:137], v[40:41], v[176:177]
	v_pk_fma_f32 v[36:37], v[134:135], v[36:37], v[178:179]
	v_cvt_pk_bf16_f32 v40, v40, v41
	v_cvt_pk_bf16_f32 v41, v36, v37
	v_pk_mul_f32 v[36:37], v[150:151], v[44:45] op_sel_hi:[1,0]
	v_pk_mul_f32 v[34:35], v[34:35], v[44:45] op_sel_hi:[1,0]
	v_pk_fma_f32 v[36:37], v[140:141], v[36:37], v[238:239]
	v_pk_fma_f32 v[34:35], v[138:139], v[34:35], v[240:241]
	v_cvt_pk_bf16_f32 v36, v36, v37
	v_cvt_pk_bf16_f32 v37, v34, v35
	v_pk_mul_f32 v[34:35], v[38:39], v[44:45] op_sel_hi:[1,0]
	v_pk_mul_f32 v[32:33], v[32:33], v[44:45] op_sel_hi:[1,0]
	v_pk_fma_f32 v[34:35], v[144:145], v[34:35], v[242:243]
	v_pk_fma_f32 v[32:33], v[142:143], v[32:33], v[244:245]
	v_lshl_add_u64 v[42:43], v[42:43], 0, v[146:147]
	v_cvt_pk_bf16_f32 v34, v34, v35
	v_cvt_pk_bf16_f32 v35, v32, v33
	v_add_u32_e32 v32, 0xb0, v148
	global_store_dwordx2 v[42:43], v[34:35], off offset:288
	v_ashrrev_i32_e32 v33, 31, v32
	v_mov_b32_e32 v34, v45
	v_pk_mul_f32 v[96:97], v[96:97], v[94:95] op_sel_hi:[1,0]
	v_pk_mul_f32 v[98:99], v[98:99], v[94:95] op_sel_hi:[1,0]
	v_pk_mul_f32 v[80:81], v[80:81], v[78:79] op_sel_hi:[1,0]
	v_pk_mul_f32 v[82:83], v[82:83], v[78:79] op_sel_hi:[1,0]
	v_pk_mul_f32 v[60:61], v[60:61], v[66:67] op_sel_hi:[1,0]
	v_pk_mul_f32 v[62:63], v[62:63], v[66:67] op_sel_hi:[1,0]
	v_lshlrev_b64 v[32:33], 11, v[32:33]
	v_pk_mul_f32 v[28:29], v[28:29], v[34:35] op_sel_hi:[1,0]
	v_pk_mul_f32 v[22:23], v[22:23], v[34:35] op_sel_hi:[1,0]
	v_pk_fma_f32 v[126:127], v[132:133], v[126:127], v[246:247]
	v_pk_fma_f32 v[98:99], v[130:131], v[98:99], v[248:249]
	v_pk_fma_f32 v[96:97], v[132:133], v[96:97], v[246:247]
	v_pk_fma_f32 v[82:83], v[130:131], v[82:83], v[248:249]
	v_pk_fma_f32 v[80:81], v[132:133], v[80:81], v[246:247]
	v_pk_fma_f32 v[62:63], v[130:131], v[62:63], v[248:249]
	v_pk_fma_f32 v[60:61], v[132:133], v[60:61], v[246:247]
	v_lshl_add_u64 v[32:33], s[0:1], 0, v[32:33]
	v_pk_fma_f32 v[2:3], v[130:131], v[22:23], v[248:249]
	v_pk_fma_f32 v[0:1], v[132:133], v[28:29], v[246:247]
	v_cvt_pk_bf16_f32 v80, v80, v81
	v_cvt_pk_bf16_f32 v81, v82, v83
	v_lshl_add_u64 v[32:33], v[32:33], 0, v[146:147]
	v_cvt_pk_bf16_f32 v0, v0, v1
	v_cvt_pk_bf16_f32 v1, v2, v3
	global_store_dwordx2 v[76:77], v[80:81], off
	v_pk_mul_f32 v[72:73], v[72:73], v[78:79] op_sel_hi:[1,0]
	v_pk_mul_f32 v[74:75], v[74:75], v[78:79] op_sel_hi:[1,0]
	global_store_dwordx2 v[32:33], v[0:1], off
	v_pk_mul_f32 v[0:1], v[26:27], v[34:35] op_sel_hi:[1,0]
	v_pk_mul_f32 v[2:3], v[20:21], v[34:35] op_sel_hi:[1,0]
	v_pk_fma_f32 v[74:75], v[134:135], v[74:75], v[178:179]
	v_pk_fma_f32 v[72:73], v[136:137], v[72:73], v[176:177]
	v_pk_fma_f32 v[2:3], v[134:135], v[2:3], v[178:179]
	v_pk_fma_f32 v[0:1], v[136:137], v[0:1], v[176:177]
	v_cvt_pk_bf16_f32 v72, v72, v73
	v_cvt_pk_bf16_f32 v73, v74, v75
	v_cvt_pk_bf16_f32 v0, v0, v1
	v_cvt_pk_bf16_f32 v1, v2, v3
	global_store_dwordx2 v[76:77], v[72:73], off offset:32
	v_pk_mul_f32 v[68:69], v[68:69], v[78:79] op_sel_hi:[1,0]
	v_pk_mul_f32 v[70:71], v[70:71], v[78:79] op_sel_hi:[1,0]
	global_store_dwordx2 v[32:33], v[0:1], off offset:32
	v_pk_mul_f32 v[0:1], v[24:25], v[34:35] op_sel_hi:[1,0]
	v_pk_mul_f32 v[2:3], v[16:17], v[34:35] op_sel_hi:[1,0]
	v_pk_fma_f32 v[70:71], v[138:139], v[70:71], v[240:241]
	v_pk_fma_f32 v[68:69], v[140:141], v[68:69], v[238:239]
	v_pk_fma_f32 v[2:3], v[138:139], v[2:3], v[240:241]
	v_pk_fma_f32 v[0:1], v[140:141], v[0:1], v[238:239]
	v_cvt_pk_bf16_f32 v68, v68, v69
	v_cvt_pk_bf16_f32 v69, v70, v71
	v_cvt_pk_bf16_f32 v0, v0, v1
	v_cvt_pk_bf16_f32 v1, v2, v3
	v_pk_mul_f32 v[88:89], v[88:89], v[94:95] op_sel_hi:[1,0]
	v_pk_mul_f32 v[90:91], v[90:91], v[94:95] op_sel_hi:[1,0]
	v_pk_mul_f32 v[84:85], v[84:85], v[94:95] op_sel_hi:[1,0]
	v_pk_mul_f32 v[86:87], v[86:87], v[94:95] op_sel_hi:[1,0]
	global_store_dwordx2 v[76:77], v[68:69], off offset:256
	v_pk_mul_f32 v[56:57], v[56:57], v[66:67] op_sel_hi:[1,0]
	v_pk_mul_f32 v[58:59], v[58:59], v[66:67] op_sel_hi:[1,0]
	v_pk_mul_f32 v[52:53], v[52:53], v[66:67] op_sel_hi:[1,0]
	v_pk_mul_f32 v[54:55], v[54:55], v[66:67] op_sel_hi:[1,0]
	global_store_dwordx2 v[32:33], v[0:1], off offset:256
	v_pk_mul_f32 v[0:1], v[30:31], v[34:35] op_sel_hi:[1,0]
	v_pk_mul_f32 v[2:3], v[18:19], v[34:35] op_sel_hi:[1,0]
	v_pk_fma_f32 v[124:125], v[134:135], v[124:125], v[178:179]
	v_pk_fma_f32 v[122:123], v[136:137], v[122:123], v[176:177]
	v_pk_fma_f32 v[90:91], v[134:135], v[90:91], v[178:179]
	v_pk_fma_f32 v[88:89], v[136:137], v[88:89], v[176:177]
	v_pk_fma_f32 v[86:87], v[138:139], v[86:87], v[240:241]
	v_pk_fma_f32 v[84:85], v[140:141], v[84:85], v[238:239]
	v_pk_fma_f32 v[58:59], v[134:135], v[58:59], v[178:179]
	v_pk_fma_f32 v[56:57], v[136:137], v[56:57], v[176:177]
	v_pk_fma_f32 v[54:55], v[138:139], v[54:55], v[240:241]
	v_pk_fma_f32 v[52:53], v[140:141], v[52:53], v[238:239]
	v_pk_fma_f32 v[2:3], v[142:143], v[2:3], v[244:245]
	v_pk_fma_f32 v[0:1], v[144:145], v[0:1], v[242:243]
	v_cvt_pk_bf16_f32 v126, v126, v127
	v_cvt_pk_bf16_f32 v127, v128, v129
	v_cvt_pk_bf16_f32 v122, v122, v123
	v_cvt_pk_bf16_f32 v123, v124, v125
	v_cvt_pk_bf16_f32 v118, v118, v119
	v_cvt_pk_bf16_f32 v119, v120, v121
	v_cvt_pk_bf16_f32 v96, v96, v97
	v_cvt_pk_bf16_f32 v97, v98, v99
	v_cvt_pk_bf16_f32 v88, v88, v89
	v_cvt_pk_bf16_f32 v89, v90, v91
	v_cvt_pk_bf16_f32 v84, v84, v85
	v_cvt_pk_bf16_f32 v85, v86, v87
	v_cvt_pk_bf16_f32 v60, v60, v61
	v_cvt_pk_bf16_f32 v61, v62, v63
	v_cvt_pk_bf16_f32 v56, v56, v57
	v_cvt_pk_bf16_f32 v57, v58, v59
	v_cvt_pk_bf16_f32 v52, v52, v53
	v_cvt_pk_bf16_f32 v53, v54, v55
	v_cvt_pk_bf16_f32 v0, v0, v1
	v_cvt_pk_bf16_f32 v1, v2, v3
	global_store_dwordx2 v[164:165], v[126:127], off
	global_store_dwordx2 v[164:165], v[122:123], off offset:32
	global_store_dwordx2 v[164:165], v[118:119], off offset:256
	global_store_dwordx2 v[92:93], v[96:97], off
	global_store_dwordx2 v[92:93], v[88:89], off offset:32
	global_store_dwordx2 v[92:93], v[84:85], off offset:256
	global_store_dwordx2 v[64:65], v[60:61], off
	global_store_dwordx2 v[64:65], v[56:57], off offset:32
	global_store_dwordx2 v[64:65], v[52:53], off offset:256
	global_store_dwordx2 v[42:43], v[46:47], off
	global_store_dwordx2 v[42:43], v[40:41], off offset:32
	global_store_dwordx2 v[42:43], v[36:37], off offset:256
	global_store_dwordx2 v[32:33], v[0:1], off offset:288
	v_mov_b32_e32 v8, v238
	v_mov_b32_e32 v9, v239
	v_mov_b32_e32 v10, v240
	v_mov_b32_e32 v11, v241
	v_mov_b32_e32 v12, v242
	v_mov_b32_e32 v13, v243
	v_mov_b32_e32 v14, v244
	v_mov_b32_e32 v15, v245
	v_mov_b32_e32 v4, v176
	v_mov_b32_e32 v5, v177
	v_mov_b32_e32 v6, v178
	v_mov_b32_e32 v7, v179
